# adds: diff-attn P1 issue balancing - K-pointer/M0 SALU and the 4 LDS-DMAs spread over the empty QK MFMA gaps, P2/P3 bf16 packing deferred into the MFMA2/MFMA3 gaps of the next tile (exps land in freed
# speedup vs baseline: 1.0935x; 1.0102x over previous
; DI unsigned pk2(float lo, float hi) { f32x2 v = {lo, hi}; bf16v2_t b = __builtin_convertvector(v, bf16v2_t); return __builtin_bit_cast(unsigned, b); }
; #define VLOAD(dst, sbv, q) do { _Pragma("unroll") for (int d_ = 0; d_ < 4; ++d_) dst[d_] = *(const lds_bf16x8*)((sbv) + vo[q] + d_ * 4096); } while (0)
; template <int Q>
; DI float exp_pack1(const f32x16 (&st)[2], float m, bf16x8& Pq) {
;   float e[8]; float ps = 0.f;
; #pragma unroll
;   for (int j = 0; j < 8; ++j) { e[j] = __builtin_amdgcn_exp2f(__builtin_fmaf(st[Q >> 1][8 * (Q & 1) + j], QK_C, -m)); ps += e[j]; }
;   u32x4 pw; pw.x = pk2(e[0], e[1]); pw.y = pk2(e[2], e[3]); pw.z = pk2(e[4], e[5]); pw.w = pk2(e[6], e[7]);
;   Pq = __builtin_bit_cast(bf16x8, pw);
;   return ps;
; }
; DI float exp_pack(const f32x16 (&st)[2], float m, bf16x8 (&Pn)[4]) {
;   return (exp_pack1<0>(st, m, Pn[0]) + exp_pack1<1>(st, m, Pn[1])) + (exp_pack1<2>(st, m, Pn[2]) + exp_pack1<3>(st, m, Pn[3]));
; }
; DI void diff_unit(KP p, int l, int b, int h, int qb, int isctx, float lamv, float lam_init, char* ldsc) {
;     ...
;   bf16x8 P[4];
;   {
;     f32x16 st[2];
;     qk_tile(qf, L + comp * 8192, ko, st);
;     m = tile_max(st);
;     lsum = exp_pack(st, m, P);
;   }
;   int stg = 0;
;   bool need = false; float alpha = 1.f;
;   if (w >= 4) __builtin_amdgcn_s_setprio(1);
;   bf16x8 vA[4], vB[4];
;   VLOAD(vA, L + 16384, 0); VLOAD(vB, L + 16384, 1);
.LBB0_470:
	v_and_b32_e32 v133, 63, v38
	v_max_f32_e32 v38, v43, v43
	v_max_f32_e32 v42, v42, v42
	v_max_f32_e32 v153, v42, v38
	v_sub_f32_e32 v252, 0, v153
	v_mov_b32_e32 v253, v252
	v_fma_f32 v2, v2, 1.0, -v153
	v_fma_f32 v3, v3, 1.0, -v153
	v_exp_f32_e32 v2, v2
	v_exp_f32_e32 v3, v3
	v_fma_f32 v10, v10, 1.0, -v153
	v_exp_f32_e32 v10, v10
	v_fma_f32 v11, v11, 1.0, -v153
	v_fma_f32 v4, v4, 1.0, -v153
	v_exp_f32_e32 v11, v11
	v_fma_f32 v12, v12, 1.0, -v153
	v_exp_f32_e32 v4, v4
	v_fma_f32 v5, v5, 1.0, -v153
	v_exp_f32_e32 v12, v12
	v_fma_f32 v13, v13, 1.0, -v153
	v_exp_f32_e32 v5, v5
	v_fma_f32 v6, v6, 1.0, -v153
	v_cvt_pk_bf16_f32 v66, v2, v3
	v_exp_f32_e32 v13, v13
	v_fma_f32 v14, v14, 1.0, -v153
	v_add_f32_e32 v2, 0, v2
	v_exp_f32_e32 v6, v6
	v_fma_f32 v7, v7, 1.0, -v153
	v_exp_f32_e32 v14, v14
	v_fma_f32 v15, v15, 1.0, -v153
	v_add_f32_e32 v2, v3, v2
	v_add_f32_e32 v3, 0, v10
	v_exp_f32_e32 v7, v7
	v_fma_f32 v8, v8, 1.0, -v153
	v_exp_f32_e32 v15, v15
	v_fma_f32 v16, v16, 1.0, -v153
	v_add_f32_e32 v3, v11, v3
	v_exp_f32_e32 v8, v8
	v_fma_f32 v9, v9, 1.0, -v153
	v_exp_f32_e32 v16, v16
	v_fma_f32 v17, v17, 1.0, -v153
	v_add_f32_e32 v2, v4, v2
	v_add_f32_e32 v3, v12, v3
	v_exp_f32_e32 v9, v9
	v_exp_f32_e32 v17, v17
	v_fma_f32 v18, v18, 1.0, -v153
	v_fma_f32 v26, v26, 1.0, -v153
	v_add_f32_e32 v2, v5, v2
	v_add_f32_e32 v3, v13, v3
	v_exp_f32_e32 v18, v18
	v_fma_f32 v19, v19, 1.0, -v153
	v_exp_f32_e32 v26, v26
	v_fma_f32 v27, v27, 1.0, -v153
	v_add_f32_e32 v2, v6, v2
	v_add_f32_e32 v3, v14, v3
	v_exp_f32_e32 v19, v19
	v_fma_f32 v20, v20, 1.0, -v153
	v_exp_f32_e32 v27, v27
	v_fma_f32 v28, v28, 1.0, -v153
	v_add_f32_e32 v2, v7, v2
	v_add_f32_e32 v3, v15, v3
	v_exp_f32_e32 v20, v20
	v_fma_f32 v21, v21, 1.0, -v153
	v_exp_f32_e32 v28, v28
	v_fma_f32 v29, v29, 1.0, -v153
	v_add_f32_e32 v2, v8, v2
	v_add_f32_e32 v3, v16, v3
	v_exp_f32_e32 v21, v21
	v_fma_f32 v22, v22, 1.0, -v153
	v_exp_f32_e32 v29, v29
	v_fma_f32 v30, v30, 1.0, -v153
	v_add_f32_e32 v2, v9, v2
	v_add_f32_e32 v3, v17, v3
	v_cvt_pk_bf16_f32 v67, v4, v5
	v_exp_f32_e32 v22, v22
	v_fma_f32 v23, v23, 1.0, -v153
	v_exp_f32_e32 v30, v30
	v_fma_f32 v31, v31, 1.0, -v153
	v_add_f32_e32 v2, v2, v3
	v_add_f32_e32 v3, 0, v18
	v_add_f32_e32 v4, 0, v26
	v_exp_f32_e32 v23, v23
	v_fma_f32 v24, v24, 1.0, -v153
	v_exp_f32_e32 v31, v31
	v_fma_f32 v32, v32, 1.0, -v153
	v_add_f32_e32 v3, v19, v3
	v_add_f32_e32 v4, v27, v4
	v_exp_f32_e32 v24, v24
	v_fma_f32 v25, v25, 1.0, -v153
	v_exp_f32_e32 v32, v32
	v_fma_f32 v33, v33, 1.0, -v153
	v_add_f32_e32 v3, v20, v3
	v_add_f32_e32 v4, v28, v4
	v_exp_f32_e32 v25, v25
	v_exp_f32_e32 v33, v33
	v_add_f32_e32 v3, v21, v3
	v_add_f32_e32 v4, v29, v4
	v_add_f32_e32 v3, v22, v3
	v_add_f32_e32 v4, v30, v4
	v_add_f32_e32 v3, v23, v3
	v_add_f32_e32 v4, v31, v4
	v_add_f32_e32 v3, v24, v3
	v_add_f32_e32 v4, v32, v4
	v_lshlrev_b32_e32 v35, 7, v35
	v_bitop3_b32 v38, v144, v34, 7 bitop3:0x78
	v_add_f32_e32 v3, v25, v3
	v_add_f32_e32 v4, v33, v4
	v_lshl_or_b32 v150, v38, 4, v35
	v_bitop3_b32 v38, v39, v34, 7 bitop3:0x78
	v_add_f32_e32 v3, v3, v4
	v_lshl_or_b32 v151, v38, 4, v35
	v_add_f32_e32 v152, v2, v3
	v_add_u32_e32 v2, 0, v150
	ds_read_b128 v[86:89], v2 offset:16384
	ds_read_b128 v[82:85], v2 offset:20480
	ds_read_b128 v[78:81], v2 offset:24576
	ds_read_b128 v[74:77], v2 offset:28672
	v_add_u32_e32 v2, 0, v151
	s_add_i32 s2, s18, s17
	s_mul_i32 s15, s15, 0x21000
	ds_read_b128 v[126:129], v2 offset:16384
	ds_read_b128 v[122:125], v2 offset:20480
	ds_read_b128 v[94:97], v2 offset:24576
	ds_read_b128 v[90:93], v2 offset:28672
	v_lshl_add_u64 v[136:137], s[10:11], 0, v[0:1]
	s_mov_b64 s[22:23], s[10:11]
	v_add_u32_e32 v244, 0x800, v0
	v_add_u32_e32 v245, 0x880, v0
	s_add_i32 s10, s16, 0xffffff80
	s_mul_hi_i32 s11, s2, 0x4200
	s_mulk_i32 s2, 0x4200
	v_mov_b32_e32 v0, s15
	v_mad_u32_u24 v0, v36, s65, v0
	s_add_u32 s4, s4, s2
	v_or_b32_e32 v0, v0, v37
	s_addc_u32 s5, s5, s11
	v_cvt_pk_bf16_f32 v72, v14, v15
	v_bitop3_b32 v38, v40, v34, 7 bitop3:0x78
	v_bitop3_b32 v34, v41, v34, 7 bitop3:0x78
	v_lshl_add_u64 v[2:3], s[4:5], 0, v[0:1]
	s_add_u32 s20, s4, 0x180
	s_addc_u32 s21, s5, 0
	v_mov_b32_e32 v246, v0
	v_add_u32_e32 v247, 0x108000, v0
	s_mov_b64 s[4:5], 0x108180
	v_mov_b32_e32 v14, v1
	v_mov_b32_e32 v15, v1
	v_cvt_pk_bf16_f32 v68, v6, v7
	v_cvt_pk_bf16_f32 v69, v8, v9
	v_cvt_pk_bf16_f32 v70, v10, v11
	v_cvt_pk_bf16_f32 v71, v12, v13
	v_cvt_pk_bf16_f32 v118, v18, v19
	v_cvt_pk_bf16_f32 v119, v20, v21
	v_cvt_pk_bf16_f32 v120, v22, v23
	v_cvt_pk_bf16_f32 v121, v24, v25
	v_cvt_pk_bf16_f32 v114, v26, v27
	v_cvt_pk_bf16_f32 v115, v28, v29
	v_cvt_pk_bf16_f32 v116, v30, v31
	v_cvt_pk_bf16_f32 v117, v32, v33
	v_lshl_or_b32 v149, v38, 4, v35
	v_lshl_or_b32 v146, v34, 4, v35
	v_lshl_add_u64 v[138:139], v[2:3], 0, s[4:5]
	v_mov_b32_e32 v0, v1
	v_mov_b32_e32 v2, v1
	v_mov_b32_e32 v3, v1
	v_mov_b32_e32 v4, v1
	v_mov_b32_e32 v5, v1
	v_mov_b32_e32 v6, v1
	v_mov_b32_e32 v7, v1
	v_mov_b32_e32 v8, v1
	v_mov_b32_e32 v9, v1
	v_mov_b32_e32 v10, v1
	v_mov_b32_e32 v11, v1
	v_mov_b32_e32 v12, v1
	v_mov_b32_e32 v13, v1
	v_mov_b64_e32 v[64:65], v[14:15]
	v_mov_b64_e32 v[48:49], v[14:15]
	v_mov_b64_e32 v[32:33], v[14:15]
	v_cvt_pk_bf16_f32 v73, v16, v17
	v_mov_b64_e32 v[62:63], v[12:13]
	v_mov_b64_e32 v[60:61], v[10:11]
	v_mov_b64_e32 v[58:59], v[8:9]
	v_mov_b64_e32 v[56:57], v[6:7]
	v_mov_b64_e32 v[54:55], v[4:5]
	v_mov_b64_e32 v[52:53], v[2:3]
	v_mov_b64_e32 v[50:51], v[0:1]
	v_mov_b64_e32 v[46:47], v[12:13]
	v_mov_b64_e32 v[44:45], v[10:11]
	v_mov_b64_e32 v[42:43], v[8:9]
	v_mov_b64_e32 v[40:41], v[6:7]
	v_mov_b64_e32 v[38:39], v[4:5]
	v_mov_b64_e32 v[36:37], v[2:3]
	v_mov_b64_e32 v[34:35], v[0:1]
	v_mov_b64_e32 v[30:31], v[12:13]
	v_mov_b64_e32 v[28:29], v[10:11]
	v_mov_b64_e32 v[26:27], v[8:9]
	v_mov_b64_e32 v[24:25], v[6:7]
	v_mov_b64_e32 v[22:23], v[4:5]
	v_mov_b64_e32 v[20:21], v[2:3]
	v_mov_b64_e32 v[18:19], v[0:1]
	v_mov_b64_e32 v[16:17], v[14:15]
	v_ashrrev_i32_e32 v135, 31, v134
	v_mov_b32_e32 v140, 1.0
	s_mov_b64 s[4:5], 0
	s_mov_b32 s17, 0
	v_mov_b64_e32 v[14:15], v[12:13]
	v_mov_b64_e32 v[12:13], v[10:11]
	v_mov_b64_e32 v[10:11], v[8:9]
	v_mov_b64_e32 v[8:9], v[6:7]
	v_mov_b64_e32 v[6:7], v[4:5]
	v_mov_b64_e32 v[4:5], v[2:3]
	v_mov_b64_e32 v[2:3], v[0:1]
	s_mov_b32 s11, 0
	v_mov_b32_e32 v153, 0
	s_add_i32 s18, s14, 0x8000
	v_add_u32_e32 v136, s18, v141
	v_add_u32_e32 v137, s18, v145
	v_add_u32_e32 v138, s18, v147
	v_add_u32_e32 v139, s18, v148
	v_mov_b32_e32 v248, v149
	v_mov_b32_e32 v255, v146
	v_lshlrev_b32_e32 v228, 16, v118
	v_and_b32_e32 v229, 0xffff0000, v118
	v_lshlrev_b32_e32 v230, 16, v119
	v_and_b32_e32 v231, 0xffff0000, v119
	v_lshlrev_b32_e32 v232, 16, v120
	v_and_b32_e32 v233, 0xffff0000, v120
	v_lshlrev_b32_e32 v234, 16, v121
	v_and_b32_e32 v235, 0xffff0000, v121
	v_lshlrev_b32_e32 v236, 16, v114
	v_and_b32_e32 v237, 0xffff0000, v114
	v_lshlrev_b32_e32 v238, 16, v115
	v_and_b32_e32 v239, 0xffff0000, v115
	v_lshlrev_b32_e32 v240, 16, v116
	v_and_b32_e32 v241, 0xffff0000, v116
	v_lshlrev_b32_e32 v242, 16, v117
	v_and_b32_e32 v243, 0xffff0000, v117

; #define MFMA32(a, b, c) __builtin_amdgcn_mfma_f32_32x32x16_bf16((a), (b), (c), 0, 0, 0)
; #define VLOAD(dst, sbv, q) do { _Pragma("unroll") for (int d_ = 0; d_ < 4; ++d_) dst[d_] = *(const lds_bf16x8*)((sbv) + vo[q] + d_ * 4096); } while (0)
; #define FENCE __builtin_amdgcn_sched_barrier(0)
; DI void diff_unit(KP p, int l, int b, int h, int qb, int isctx, float lamv, float lam_init, char* ldsc) {
;     ...
;   for (int kt = 0; kt < nt - 1; ++kt) {
;     asm volatile("s_waitcnt vmcnt(0)" ::: "memory");
;     __builtin_amdgcn_s_barrier();
;     const int stg1 = stg == 2 ? 0 : stg + 1;
;     if (kt + 2 < nt) { const int s2_ = stg >= 1 ? stg - 1 : 2; DISSUE(kt + 2, s2_); }
;     if (need) {
; #pragma unroll
;       for (int d = 0; d < 4; ++d) o[d] *= alpha;
;     }
;     const lds_u8* sbv = L + stg * STG + 16384;
;     const lds_u8* sbk = L + stg1 * STG + comp * 8192;
;     bf16x8 kf[2][4];
;     f32x16 st[2];
; #pragma unroll
;     for (int t = 0; t < 2; ++t)
; #pragma unroll
;       for (int ks = 0; ks < 4; ++ks) kf[t][ks] = *(const lds_bf16x8*)(sbk + ko[ks] + t * 4096);
;     FENCE;
;     pv_grp(o, vA, P[0]); pv_grp(o, vB, P[1]);
;     VLOAD(vA, sbv, 2); VLOAD(vB, sbv, 3);
;     FENCE;
; #pragma unroll
;     for (int i = 0; i < 16; ++i) { st[0][i] = 0.f; st[1][i] = 0.f; }
; #pragma unroll
;     for (int ks = 0; ks < 4; ++ks) st[0] = MFMA32(kf[0][ks], qf[ks], st[0]);
; #pragma unroll
;     for (int ks = 0; ks < 4; ++ks) st[1] = MFMA32(kf[1][ks], qf[ks], st[1]);
;     FENCE;
;     pv_grp(o, vA, P[2]);
;     const float mx = tile_max(st);
;     need = !__all(mx <= m + 8.0f);
;     const float mn = need ? fmaxf(m, mx) : m;
;     alpha = __builtin_amdgcn_exp2f(m - mn);
;     FENCE;
;     float ps = exp_pack1<0>(st, mn, P[0]);
;     ps += exp_pack1<1>(st, mn, P[1]);
;     ps += exp_pack1<2>(st, mn, P[2]);
;     pv_grp(o, vB, P[3]);
;     ps += exp_pack1<3>(st, mn, P[3]);
; #pragma unroll
;     for (int q = 0; q < 4; ++q) { __builtin_amdgcn_sched_group_barrier(0x402, 18, 0); __builtin_amdgcn_sched_group_barrier(0x008, 1, 0); }
.LBB0_475:
.LBB0_477:
	ds_read_b128 v[154:157], v136
	ds_read_b128 v[192:195], v136 offset:4096
	ds_read_b128 v[196:199], v137
	ds_read_b128 v[200:203], v137 offset:4096
	ds_read_b128 v[204:207], v138
	ds_read_b128 v[208:211], v138 offset:4096
	ds_read_b128 v[212:215], v139
	ds_read_b128 v[216:219], v139 offset:4096
	s_waitcnt lgkmcnt(8)
	v_mfma_f32_32x32x16_bf16 v[50:65], v[86:89], v[66:69], v[50:65]
	s_add_i32 s2, s17, 1
	s_and_b32 s16, s2, 3
	s_lshl_b32 s15, s16, 15
	ds_read_b128 v[220:223], v248 offset:24576
	ds_read_b128 v[224:227], v248 offset:28672
	v_mfma_f32_32x32x16_bf16 v[34:49], v[82:85], v[66:69], v[34:49]
	v_cvt_pk_bf16_f32 v118, v228, v229
	v_cvt_pk_bf16_f32 v119, v230, v231
	v_cvt_pk_bf16_f32 v120, v232, v233
	v_cvt_pk_bf16_f32 v121, v234, v235
	v_mfma_f32_32x32x16_bf16 v[18:33], v[78:81], v[66:69], v[18:33]
	v_cvt_pk_bf16_f32 v114, v236, v237
	v_cvt_pk_bf16_f32 v115, v238, v239
	v_cvt_pk_bf16_f32 v116, v240, v241
	v_cvt_pk_bf16_f32 v117, v242, v243
	v_mfma_f32_32x32x16_bf16 v[2:17], v[74:77], v[66:69], v[2:17]
	v_mov_b64_e32 v[66:67], v[252:253]
	v_mov_b64_e32 v[68:69], v[252:253]
	v_mov_b64_e32 v[74:75], v[252:253]
	v_mfma_f32_32x32x16_bf16 v[50:65], v[126:129], v[70:73], v[50:65]
	v_mov_b64_e32 v[76:77], v[252:253]
	v_mov_b64_e32 v[78:79], v[252:253]
	v_mov_b64_e32 v[80:81], v[252:253]
	ds_read_b128 v[126:129], v248 offset:20480
	v_mfma_f32_32x32x16_bf16 v[34:49], v[122:125], v[70:73], v[34:49]
	ds_read_b128 v[122:125], v248 offset:16384
	ds_read_b128 v[228:231], v255 offset:16384
	ds_read_b128 v[232:235], v255 offset:20480
	v_mfma_f32_32x32x16_bf16 v[18:33], v[94:97], v[70:73], v[18:33]
	ds_read_b128 v[236:239], v255 offset:24576
	ds_read_b128 v[240:243], v255 offset:28672
	v_mfma_f32_32x32x16_bf16 v[2:17], v[90:93], v[70:73], v[2:17]
	v_mov_b64_e32 v[70:71], v[252:253]
	v_mov_b64_e32 v[72:73], v[252:253]
	s_add_i32 s18, s3, 0xc0
	s_add_i32 s19, s10, 64
	s_cmp_eq_u32 s11, 0
	s_cselect_b32 s19, s18, s19
	s_add_i32 s11, s11, 1
	s_add_i32 s10, s10, 64
	s_waitcnt lgkmcnt(8)
	v_mfma_f32_32x32x16_bf16 v[82:97], v[154:157], v[98:101], v[66:81]
	s_mul_i32 s19, s19, 0x1600
	s_add_u32 s18, s22, s19
	s_addc_u32 s19, s23, 0
	s_add_i32 s24, s17, 3
	s_and_b32 s24, s24, 3
	s_lshl_b32 s24, s24, 15
	s_add_i32 s24, s13, s24
	s_mov_b32 m0, s24
	v_mfma_f32_32x32x16_bf16 v[66:81], v[192:195], v[98:101], v[66:81]
	global_load_lds_dwordx4 v244, s[18:19]
	s_add_i32 m0, s24, 0x2000
	v_mfma_f32_32x32x16_bf16 v[66:81], v[200:203], v[102:105], v[66:81]
	global_load_lds_dwordx4 v245, s[18:19]
	s_add_i32 m0, s24, 0x4000
	v_mfma_f32_32x32x16_bf16 v[82:97], v[196:199], v[102:105], v[82:97]
	global_load_lds_dwordx4 v246, s[20:21]
	s_add_i32 m0, s24, 0x6000
	v_mfma_f32_32x32x16_bf16 v[66:81], v[208:211], v[106:109], v[66:81]
	global_load_lds_dwordx4 v247, s[20:21]
	s_add_u32 s20, s20, 0x80
	s_addc_u32 s21, s21, 0
	v_mfma_f32_32x32x16_bf16 v[82:97], v[204:207], v[106:109], v[82:97]
	s_add_i32 s18, s16, 1
	s_and_b32 s18, s18, 3
	s_lshl_b32 s18, s18, 15
	s_add_i32 s18, s18, s14
	v_mfma_f32_32x32x16_bf16 v[66:81], v[216:219], v[110:113], v[66:81]
	v_mfma_f32_32x32x16_bf16 v[82:97], v[212:215], v[110:113], v[82:97]
	s_waitcnt lgkmcnt(0)
	v_mfma_f32_32x32x16_bf16 v[50:65], v[122:125], v[118:121], v[50:65]
	v_add_u32_e32 v251, s15, v150
	v_add_u32_e32 v249, s15, v151
	v_add_u32_e32 v136, s18, v141
	v_add_u32_e32 v137, s18, v145
	v_add_u32_e32 v138, s18, v147
	v_add_u32_e32 v139, s18, v148
	s_mov_b32 s17, s16
	s_cmpk_lg_i32 s11, 0x83
	v_add_u32_e32 v248, s15, v149
	v_add_u32_e32 v255, s15, v146
	v_mfma_f32_32x32x16_bf16 v[34:49], v[126:129], v[118:121], v[34:49]
	v_exp_f32_e32 v122, v82
	v_exp_f32_e32 v124, v83
	v_exp_f32_e32 v126, v84
	v_exp_f32_e32 v128, v85
	v_exp_f32_e32 v156, v86
	v_mfma_f32_32x32x16_bf16 v[18:33], v[220:223], v[118:121], v[18:33]
	v_exp_f32_e32 v192, v87
	v_exp_f32_e32 v194, v88
	v_exp_f32_e32 v196, v89
	v_exp_f32_e32 v123, v90
	v_exp_f32_e32 v125, v91
	v_mfma_f32_32x32x16_bf16 v[2:17], v[224:227], v[118:121], v[2:17]
	v_exp_f32_e32 v127, v92
	v_exp_f32_e32 v129, v93
	v_exp_f32_e32 v157, v94
	v_exp_f32_e32 v193, v95
	v_exp_f32_e32 v195, v96
	v_mfma_f32_32x32x16_bf16 v[50:65], v[228:231], v[114:117], v[50:65]
	v_exp_f32_e32 v197, v97
	v_exp_f32_e32 v228, v66
	v_exp_f32_e32 v229, v67
	v_exp_f32_e32 v230, v68
	v_exp_f32_e32 v231, v69
	v_mfma_f32_32x32x16_bf16 v[34:49], v[232:235], v[114:117], v[34:49]
	v_exp_f32_e32 v232, v70
	v_exp_f32_e32 v233, v71
	v_exp_f32_e32 v234, v72
	v_exp_f32_e32 v235, v73
	v_pk_add_f32 v[92:93], v[124:125], v[122:123]
	v_pk_add_f32 v[92:93], v[126:127], v[92:93]
	v_mfma_f32_32x32x16_bf16 v[18:33], v[236:239], v[114:117], v[18:33]
	v_exp_f32_e32 v236, v74
	v_exp_f32_e32 v237, v75
	v_exp_f32_e32 v238, v76
	v_exp_f32_e32 v239, v77
	v_pk_add_f32 v[92:93], v[128:129], v[92:93]
	v_pk_add_f32 v[92:93], v[156:157], v[92:93]
	v_mfma_f32_32x32x16_bf16 v[2:17], v[240:243], v[114:117], v[2:17]
	v_exp_f32_e32 v240, v78
	v_exp_f32_e32 v241, v79
	v_exp_f32_e32 v242, v80
	v_exp_f32_e32 v243, v81
	v_pk_add_f32 v[92:93], v[192:193], v[92:93]
	v_pk_add_f32 v[92:93], v[194:195], v[92:93]
	v_pk_add_f32 v[92:93], v[196:197], v[92:93]
	ds_read_b128 v[78:81], v251 offset:24576
	ds_read_b128 v[74:77], v251 offset:28672
	v_pk_add_f32 v[198:199], v[228:229], v[230:231]
	v_pk_add_f32 v[198:199], v[232:233], v[198:199]
	v_pk_add_f32 v[198:199], v[234:235], v[198:199]
	v_pk_add_f32 v[198:199], v[236:237], v[198:199]
	v_pk_add_f32 v[198:199], v[238:239], v[198:199]
	v_pk_add_f32 v[198:199], v[240:241], v[198:199]
	v_pk_add_f32 v[198:199], v[242:243], v[198:199]
	v_pk_add_f32 v[198:199], v[198:199], v[92:93]
	v_max_f32_e32 v200, v198, v199
	v_cmp_lt_f32_e32 vcc, 0x43000000, v200
	s_cbranch_vccnz .Ldiff_rare
; #define VLOAD(dst, sbv, q) do { _Pragma("unroll") for (int d_ = 0; d_ < 4; ++d_) dst[d_] = *(const lds_bf16x8*)((sbv) + vo[q] + d_ * 4096); } while (0)
; #define FENCE __builtin_amdgcn_sched_barrier(0)
; DI void diff_unit(KP p, int l, int b, int h, int qb, int isctx, float lamv, float lam_init, char* ldsc) {
;     ...
;     pv_grp(o, vA, P[2]);
;     const float mx = tile_max(st);
;     need = !__all(mx <= m + 8.0f);
;     const float mn = need ? fmaxf(m, mx) : m;
;     alpha = __builtin_amdgcn_exp2f(m - mn);
;     FENCE;
;     float ps = exp_pack1<0>(st, mn, P[0]);
;     ps += exp_pack1<1>(st, mn, P[1]);
;     ps += exp_pack1<2>(st, mn, P[2]);
;     pv_grp(o, vB, P[3]);
;     ps += exp_pack1<3>(st, mn, P[3]);
; #pragma unroll
;     for (int q = 0; q < 4; ++q) { __builtin_amdgcn_sched_group_barrier(0x402, 18, 0); __builtin_amdgcn_sched_group_barrier(0x008, 1, 0); }
;     lsum = lsum * alpha + ps; m = mn;
;     FENCE;
;     { const lds_u8* sbn = L + stg1 * STG + 16384; VLOAD(vA, sbn, 0); VLOAD(vB, sbn, 1); }
;     stg = stg1;
;   }
;   __builtin_amdgcn_s_setprio(0);
;   if (need) {
; #pragma unroll
;     for (int d = 0; d < 4; ++d) o[d] *= alpha;
;   }
;   {
;     const lds_u8* sbv = L + stg * STG + 16384;
;     pv_grp(o, vA, P[0]); pv_grp(o, vB, P[1]);
;     VLOAD(vA, sbv, 2); VLOAD(vB, sbv, 3);
;     pv_grp(o, vA, P[2]);
;     pv_grp(o, vB, P[3]);
;   }
.Ldiff_rare_back:
	ds_read_b128 v[86:89], v251 offset:16384
	ds_read_b128 v[82:85], v251 offset:20480
	v_cvt_pk_bf16_f32 v66, v122, v124
	v_cvt_pk_bf16_f32 v67, v126, v128
	v_cvt_pk_bf16_f32 v70, v123, v125
	v_cvt_pk_bf16_f32 v71, v127, v129
	ds_read_b128 v[126:129], v249 offset:16384
	ds_read_b128 v[122:125], v249 offset:20480
	v_pk_add_f32 v[152:153], v[152:153], v[198:199]
	ds_read_b128 v[94:97], v249 offset:24576
	ds_read_b128 v[90:93], v249 offset:28672
	v_cvt_pk_bf16_f32 v68, v156, v192
	v_cvt_pk_bf16_f32 v69, v194, v196
	v_cvt_pk_bf16_f32 v72, v157, v193
	v_cvt_pk_bf16_f32 v73, v195, v197
	s_cbranch_scc1 .LBB0_471
	s_branch .LBB0_479
.Ldiff_rare:
	v_max3_f32 v201, v228, v229, v230
	v_max3_f32 v201, v201, v231, v232
	v_max3_f32 v201, v201, v233, v234
	v_max3_f32 v201, v201, v235, v236
	v_max3_f32 v201, v201, v237, v238
	v_max3_f32 v201, v201, v239, v240
	v_max3_f32 v201, v201, v241, v242
	v_max3_f32 v201, v201, v243, v122
	v_max3_f32 v201, v201, v123, v124
	v_max3_f32 v201, v201, v125, v126
	v_max3_f32 v201, v201, v127, v128
	v_max3_f32 v201, v201, v129, v156
	v_max3_f32 v201, v201, v157, v192
	v_max3_f32 v201, v201, v193, v194
	v_max3_f32 v201, v201, v195, v196
	v_max_f32_e32 v201, v201, v197
	v_mov_b32_e32 v202, v201
	s_nop 1
	v_permlane32_swap_b32_e32 v201, v202
	v_max_f32_e32 v201, v201, v202
	v_frexp_exp_i32_f32_e32 v202, v201
	v_max_i32_e32 v202, 0, v202
	v_sub_u32_e32 v203, 0, v202
	v_ldexp_f32 v140, 1.0, v203
	v_cvt_f32_i32_e32 v203, v202
	v_sub_f32_e32 v252, v252, v203
	v_mov_b32_e32 v253, v252
	v_pk_mul_f32 v[228:229], v[228:229], v[140:141] op_sel_hi:[1,0]
	v_pk_mul_f32 v[230:231], v[230:231], v[140:141] op_sel_hi:[1,0]
	v_pk_mul_f32 v[232:233], v[232:233], v[140:141] op_sel_hi:[1,0]
	v_pk_mul_f32 v[234:235], v[234:235], v[140:141] op_sel_hi:[1,0]
	v_pk_mul_f32 v[236:237], v[236:237], v[140:141] op_sel_hi:[1,0]
	v_pk_mul_f32 v[238:239], v[238:239], v[140:141] op_sel_hi:[1,0]
	v_pk_mul_f32 v[240:241], v[240:241], v[140:141] op_sel_hi:[1,0]
	v_pk_mul_f32 v[242:243], v[242:243], v[140:141] op_sel_hi:[1,0]
	v_pk_mul_f32 v[122:123], v[122:123], v[140:141] op_sel_hi:[1,0]
	v_pk_mul_f32 v[124:125], v[124:125], v[140:141] op_sel_hi:[1,0]
	v_pk_mul_f32 v[126:127], v[126:127], v[140:141] op_sel_hi:[1,0]
	v_pk_mul_f32 v[128:129], v[128:129], v[140:141] op_sel_hi:[1,0]
	v_pk_mul_f32 v[156:157], v[156:157], v[140:141] op_sel_hi:[1,0]
	v_pk_mul_f32 v[192:193], v[192:193], v[140:141] op_sel_hi:[1,0]
	v_pk_mul_f32 v[194:195], v[194:195], v[140:141] op_sel_hi:[1,0]
	v_pk_mul_f32 v[196:197], v[196:197], v[140:141] op_sel_hi:[1,0]
	v_pk_mul_f32 v[198:199], v[198:199], v[140:141] op_sel_hi:[1,0]
	v_pk_mul_f32 v[152:153], v[152:153], v[140:141] op_sel_hi:[1,0]
	v_pk_mul_f32 v[2:3], v[2:3], v[140:141] op_sel_hi:[1,0]
	v_pk_mul_f32 v[4:5], v[4:5], v[140:141] op_sel_hi:[1,0]
	v_pk_mul_f32 v[6:7], v[6:7], v[140:141] op_sel_hi:[1,0]
	v_pk_mul_f32 v[8:9], v[8:9], v[140:141] op_sel_hi:[1,0]
	v_pk_mul_f32 v[10:11], v[10:11], v[140:141] op_sel_hi:[1,0]
	v_pk_mul_f32 v[12:13], v[12:13], v[140:141] op_sel_hi:[1,0]
	v_pk_mul_f32 v[14:15], v[14:15], v[140:141] op_sel_hi:[1,0]
	v_pk_mul_f32 v[16:17], v[16:17], v[140:141] op_sel_hi:[1,0]
	v_pk_mul_f32 v[18:19], v[18:19], v[140:141] op_sel_hi:[1,0]
	v_pk_mul_f32 v[20:21], v[20:21], v[140:141] op_sel_hi:[1,0]
	v_pk_mul_f32 v[22:23], v[22:23], v[140:141] op_sel_hi:[1,0]
	v_pk_mul_f32 v[24:25], v[24:25], v[140:141] op_sel_hi:[1,0]
	v_pk_mul_f32 v[26:27], v[26:27], v[140:141] op_sel_hi:[1,0]
	v_pk_mul_f32 v[28:29], v[28:29], v[140:141] op_sel_hi:[1,0]
	v_pk_mul_f32 v[30:31], v[30:31], v[140:141] op_sel_hi:[1,0]
	v_pk_mul_f32 v[32:33], v[32:33], v[140:141] op_sel_hi:[1,0]
	v_pk_mul_f32 v[34:35], v[34:35], v[140:141] op_sel_hi:[1,0]
	v_pk_mul_f32 v[36:37], v[36:37], v[140:141] op_sel_hi:[1,0]
	v_pk_mul_f32 v[38:39], v[38:39], v[140:141] op_sel_hi:[1,0]
	v_pk_mul_f32 v[40:41], v[40:41], v[140:141] op_sel_hi:[1,0]
	v_pk_mul_f32 v[42:43], v[42:43], v[140:141] op_sel_hi:[1,0]
	v_pk_mul_f32 v[44:45], v[44:45], v[140:141] op_sel_hi:[1,0]
	v_pk_mul_f32 v[46:47], v[46:47], v[140:141] op_sel_hi:[1,0]
	v_pk_mul_f32 v[48:49], v[48:49], v[140:141] op_sel_hi:[1,0]
	v_pk_mul_f32 v[50:51], v[50:51], v[140:141] op_sel_hi:[1,0]
	v_pk_mul_f32 v[52:53], v[52:53], v[140:141] op_sel_hi:[1,0]
	v_pk_mul_f32 v[54:55], v[54:55], v[140:141] op_sel_hi:[1,0]
	v_pk_mul_f32 v[56:57], v[56:57], v[140:141] op_sel_hi:[1,0]
	v_pk_mul_f32 v[58:59], v[58:59], v[140:141] op_sel_hi:[1,0]
	v_pk_mul_f32 v[60:61], v[60:61], v[140:141] op_sel_hi:[1,0]
	v_pk_mul_f32 v[62:63], v[62:63], v[140:141] op_sel_hi:[1,0]
	v_pk_mul_f32 v[64:65], v[64:65], v[140:141] op_sel_hi:[1,0]
	s_branch .Ldiff_rare_back
.LBB0_479:
	v_cvt_pk_bf16_f32 v118, v228, v229
	v_cvt_pk_bf16_f32 v119, v230, v231
	v_cvt_pk_bf16_f32 v120, v232, v233
	v_cvt_pk_bf16_f32 v121, v234, v235
	v_cvt_pk_bf16_f32 v114, v236, v237
	v_cvt_pk_bf16_f32 v115, v238, v239
	v_cvt_pk_bf16_f32 v116, v240, v241
	v_cvt_pk_bf16_f32 v117, v242, v243
	v_add_f32_e32 v0, v152, v153
	s_setprio 0
	s_andn2_b64 vcc, exec, s[4:5]
	s_cbranch_vccnz .LBB0_481
	v_pk_mul_f32 v[64:65], v[64:65], v[140:141] op_sel_hi:[1,0]
	v_pk_mul_f32 v[62:63], v[62:63], v[140:141] op_sel_hi:[1,0]
	v_pk_mul_f32 v[60:61], v[60:61], v[140:141] op_sel_hi:[1,0]
	v_pk_mul_f32 v[58:59], v[58:59], v[140:141] op_sel_hi:[1,0]
	v_pk_mul_f32 v[56:57], v[56:57], v[140:141] op_sel_hi:[1,0]
	v_pk_mul_f32 v[54:55], v[54:55], v[140:141] op_sel_hi:[1,0]
	v_pk_mul_f32 v[52:53], v[52:53], v[140:141] op_sel_hi:[1,0]
	v_pk_mul_f32 v[50:51], v[50:51], v[140:141] op_sel_hi:[1,0]
	v_pk_mul_f32 v[48:49], v[48:49], v[140:141] op_sel_hi:[1,0]
	v_pk_mul_f32 v[46:47], v[46:47], v[140:141] op_sel_hi:[1,0]
	v_pk_mul_f32 v[44:45], v[44:45], v[140:141] op_sel_hi:[1,0]
	v_pk_mul_f32 v[42:43], v[42:43], v[140:141] op_sel_hi:[1,0]
	v_pk_mul_f32 v[40:41], v[40:41], v[140:141] op_sel_hi:[1,0]
	v_pk_mul_f32 v[38:39], v[38:39], v[140:141] op_sel_hi:[1,0]
	v_pk_mul_f32 v[36:37], v[36:37], v[140:141] op_sel_hi:[1,0]
	v_pk_mul_f32 v[34:35], v[34:35], v[140:141] op_sel_hi:[1,0]
	v_pk_mul_f32 v[32:33], v[32:33], v[140:141] op_sel_hi:[1,0]
	v_pk_mul_f32 v[30:31], v[30:31], v[140:141] op_sel_hi:[1,0]
	v_pk_mul_f32 v[28:29], v[28:29], v[140:141] op_sel_hi:[1,0]
	v_pk_mul_f32 v[26:27], v[26:27], v[140:141] op_sel_hi:[1,0]
	v_pk_mul_f32 v[24:25], v[24:25], v[140:141] op_sel_hi:[1,0]
	v_pk_mul_f32 v[22:23], v[22:23], v[140:141] op_sel_hi:[1,0]
	v_pk_mul_f32 v[20:21], v[20:21], v[140:141] op_sel_hi:[1,0]
	v_pk_mul_f32 v[18:19], v[18:19], v[140:141] op_sel_hi:[1,0]
	v_pk_mul_f32 v[16:17], v[16:17], v[140:141] op_sel_hi:[1,0]
	v_pk_mul_f32 v[14:15], v[14:15], v[140:141] op_sel_hi:[1,0]
	v_pk_mul_f32 v[12:13], v[12:13], v[140:141] op_sel_hi:[1,0]
	v_pk_mul_f32 v[10:11], v[10:11], v[140:141] op_sel_hi:[1,0]
	v_pk_mul_f32 v[8:9], v[8:9], v[140:141] op_sel_hi:[1,0]
	v_pk_mul_f32 v[6:7], v[6:7], v[140:141] op_sel_hi:[1,0]
	v_pk_mul_f32 v[4:5], v[4:5], v[140:141] op_sel_hi:[1,0]
	v_pk_mul_f32 v[2:3], v[2:3], v[140:141] op_sel_hi:[1,0]
